# P11 epilogue: removed 120 dead v_mov initialisations in front of row_ror DPP moves (on top of v28)
# baseline (speedup 1.0000x reference)
; DI uint2 pk4(f32x4 v) { return make_uint2(pk2(v[0], v[1]), pk2(v[2], v[3])); }
; DI float gelu_t(float x) { float u = 1.5957691216057308f * (x + 0.044715f * x * x * x); return x * __builtin_amdgcn_rcpf(1.f + __expf(-u)); }
;     DI void operator()(const f32x4 (&acc)[2][2][4][2], const pg8::Unit& u, int wr, int wc, int fr, int fq) const {
;     ...
;                     const f32x4 v = acc[ai][bj][m][0], g = acc[ai][bj][m][1];
;                     f32x4 p1, p2;
; #pragma unroll
;                     for (int r = 0; r < 4; ++r) {
;                         p1[r] = __builtin_bit_cast(float, __builtin_amdgcn_update_dpp(0, __builtin_bit_cast(int, (fr == 15) ? gprev[r] : g[r]), 0x121, 0xF, 0xF, false));
;                         p2[r] = __builtin_bit_cast(float, __builtin_amdgcn_update_dpp(0, __builtin_bit_cast(int, (fr >= 14) ? gprev[r] : g[r]), 0x122, 0xF, 0xF, false));
;                     }
;                     const int row = u.pm * 256 + ai * 128 + wr * 64 + m * 16 + fr;
;                     const int wb = row >> 6;
;                     if (m == 0 && fr < 2) {
;                         *(f32x4*)(gfirst + ((size_t)wb * 2 + fr) * FH + hc) = g;
;                         *(f32x4*)(vfirst + ((size_t)wb * 2 + fr) * FH + hc) = v;
;                     } else {
;                         f32x4 o;
;                         o[0] = gelu_t(bb.x + w0.x * p2[0] + w1.x * p1[0] + w2.x * g[0]) * v[0];
;                         o[1] = gelu_t(bb.y + w0.y * p2[1] + w1.y * p1[1] + w2.y * g[1]) * v[1];
;                         o[2] = gelu_t(bb.z + w0.z * p2[2] + w1.z * p1[2] + w2.z * g[2]) * v[2];
;                         o[3] = gelu_t(bb.w + w0.w * p2[3] + w1.w * p1[3] + w2.w * g[3]) * v[3];
;                         *(uint2*)(hid + (size_t)row * FH + hc) = pk4(o);
.LBB0_1068:
	s_or_b64 exec, exec, s[36:37]
	s_nop 0
	v_cndmask_b32_e64 v153, v128, v136, s[4:5]
	v_cndmask_b32_e64 v154, v129, v137, s[4:5]
	v_cndmask_b32_e64 v155, v130, v138, s[4:5]
	v_mov_b32_dpp v152, v153 row_ror:1 row_mask:0xf bank_mask:0xf
	v_cndmask_b32_e32 v153, v128, v136, vcc
	v_cndmask_b32_e64 v190, v131, v139, s[4:5]
	v_add_u32_e32 v168, -14, v180
	v_mov_b32_dpp v136, v153 row_ror:2 row_mask:0xf bank_mask:0xf
	s_nop 1
	v_mov_b32_dpp v153, v154 row_ror:1 row_mask:0xf bank_mask:0xf
	v_cndmask_b32_e32 v154, v129, v137, vcc
	s_nop 1
	v_mov_b32_dpp v137, v154 row_ror:2 row_mask:0xf bank_mask:0xf
	s_waitcnt vmcnt(0)
	v_pk_fma_f32 v[136:137], v[140:141], v[136:137], v[156:157]
	v_mov_b32_dpp v154, v155 row_ror:1 row_mask:0xf bank_mask:0xf
	v_cndmask_b32_e32 v155, v130, v138, vcc
	v_pk_fma_f32 v[136:137], v[144:145], v[152:153], v[136:137]
	s_nop 0
	v_mov_b32_dpp v138, v155 row_ror:2 row_mask:0xf bank_mask:0xf
	v_pk_fma_f32 v[136:137], v[128:129], v[148:149], v[136:137]
	s_nop 0
	v_mov_b32_dpp v155, v190 row_ror:1 row_mask:0xf bank_mask:0xf
	v_cndmask_b32_e32 v190, v131, v139, vcc
	v_mul_f32_e32 v152, 0x3d372713, v136
	v_mul_f32_e32 v153, 0x3d372713, v137
	v_mov_b32_dpp v139, v190 row_ror:2 row_mask:0xf bank_mask:0xf
	v_pk_fma_f32 v[138:139], v[142:143], v[138:139], v[158:159]
	v_mul_f32_e32 v152, v136, v152
	v_pk_fma_f32 v[138:139], v[146:147], v[154:155], v[138:139]
	v_mul_f32_e32 v153, v137, v153
	v_pk_fma_f32 v[138:139], v[130:131], v[150:151], v[138:139]
	v_fma_f32 v152, v136, v152, v136
	v_mul_f32_e32 v154, 0x3d372713, v138
	v_mul_f32_e32 v155, 0x3d372713, v139
	v_fma_f32 v153, v137, v153, v137
	v_mul_f32_e32 v154, v138, v154
	v_mul_f32_e32 v155, v139, v155
	v_mul_f32_e32 v152, 0xbfcc422a, v152
	v_mul_f32_e32 v153, 0xbfcc422a, v153
	v_fma_f32 v154, v138, v154, v138
	v_fma_f32 v155, v139, v155, v139
	v_mul_f32_e32 v152, 0x3fb8aa3b, v152
	v_mul_f32_e32 v153, 0x3fb8aa3b, v153
	v_mul_f32_e32 v154, 0xbfcc422a, v154
	v_mul_f32_e32 v155, 0xbfcc422a, v155
	v_exp_f32_e32 v152, v152
	v_exp_f32_e32 v153, v153
	v_mul_f32_e32 v154, 0x3fb8aa3b, v154
	v_mul_f32_e32 v155, 0x3fb8aa3b, v155
	v_exp_f32_e32 v154, v154
	v_exp_f32_e32 v155, v155
	v_add_f32_e32 v152, 1.0, v152
	v_add_f32_e32 v153, 1.0, v153
	v_rcp_f32_e32 v152, v152
	v_rcp_f32_e32 v153, v153
	v_add_f32_e32 v154, 1.0, v154
	v_add_f32_e32 v155, 1.0, v155
	v_rcp_f32_e32 v154, v154
	v_rcp_f32_e32 v155, v155
	v_pk_mul_f32 v[136:137], v[136:137], v[152:153]
	v_add_u32_e32 v190, 16, v202
	v_pk_mul_f32 v[132:133], v[132:133], v[136:137]
	v_pk_mul_f32 v[136:137], v[138:139], v[154:155]
	v_mov_b64_e32 v[138:139], s[72:73]
	v_pk_mul_f32 v[134:135], v[134:135], v[136:137]
	v_cvt_pk_bf16_f32 v136, v132, v133
	v_cvt_pk_bf16_f32 v137, v134, v135
	v_mad_i64_i32 v[132:133], s[36:37], v190, s76, v[138:139]
	v_lshlrev_b64 v[134:135], 1, v[184:185]
	v_lshl_add_u64 v[152:153], v[132:133], 0, v[134:135]
	global_store_dwordx2 v[152:153], v[136:137], off
	v_cndmask_b32_e64 v137, v120, v128, s[4:5]
	v_cndmask_b32_e64 v152, v121, v129, s[4:5]
	v_cndmask_b32_e64 v153, v122, v130, s[4:5]
	v_mov_b32_dpp v136, v137 row_ror:1 row_mask:0xf bank_mask:0xf
	v_cndmask_b32_e32 v137, v120, v128, vcc
	v_cndmask_b32_e64 v154, v123, v131, s[4:5]
	s_nop 0
	v_mov_b32_dpp v128, v137 row_ror:2 row_mask:0xf bank_mask:0xf
	s_nop 1
	v_mov_b32_dpp v137, v152 row_ror:1 row_mask:0xf bank_mask:0xf
	v_cndmask_b32_e32 v152, v121, v129, vcc
	s_nop 1
	v_mov_b32_dpp v129, v152 row_ror:2 row_mask:0xf bank_mask:0xf
	v_pk_fma_f32 v[128:129], v[140:141], v[128:129], v[156:157]
	s_nop 0
	v_mov_b32_dpp v152, v153 row_ror:1 row_mask:0xf bank_mask:0xf
	v_cndmask_b32_e32 v153, v122, v130, vcc
	v_pk_fma_f32 v[128:129], v[144:145], v[136:137], v[128:129]
	s_nop 0
	v_mov_b32_dpp v130, v153 row_ror:2 row_mask:0xf bank_mask:0xf
	v_pk_fma_f32 v[128:129], v[120:121], v[148:149], v[128:129]
	s_nop 0
	v_mov_b32_dpp v153, v154 row_ror:1 row_mask:0xf bank_mask:0xf
	v_cndmask_b32_e32 v154, v123, v131, vcc
	v_mul_f32_e32 v136, 0x3d372713, v128
	v_mul_f32_e32 v137, 0x3d372713, v129
	v_mov_b32_dpp v131, v154 row_ror:2 row_mask:0xf bank_mask:0xf
	v_pk_fma_f32 v[130:131], v[142:143], v[130:131], v[158:159]
	v_mul_f32_e32 v136, v128, v136
	v_pk_fma_f32 v[130:131], v[146:147], v[152:153], v[130:131]
	v_mul_f32_e32 v137, v129, v137
	v_pk_fma_f32 v[130:131], v[122:123], v[150:151], v[130:131]
	v_fma_f32 v136, v128, v136, v128
	v_mul_f32_e32 v152, 0x3d372713, v130
	v_mul_f32_e32 v153, 0x3d372713, v131
	v_fma_f32 v137, v129, v137, v129
	v_mul_f32_e32 v152, v130, v152
	v_mul_f32_e32 v153, v131, v153
	v_mul_f32_e32 v136, 0xbfcc422a, v136
	v_mul_f32_e32 v137, 0xbfcc422a, v137
	v_fma_f32 v152, v130, v152, v130
	v_fma_f32 v153, v131, v153, v131
	v_mul_f32_e32 v136, 0x3fb8aa3b, v136
	v_mul_f32_e32 v137, 0x3fb8aa3b, v137
	v_mul_f32_e32 v152, 0xbfcc422a, v152
	v_mul_f32_e32 v153, 0xbfcc422a, v153
	v_exp_f32_e32 v136, v136
	v_exp_f32_e32 v137, v137
	v_mul_f32_e32 v152, 0x3fb8aa3b, v152
	v_mul_f32_e32 v153, 0x3fb8aa3b, v153
	v_exp_f32_e32 v152, v152
	v_exp_f32_e32 v153, v153
	v_add_f32_e32 v136, 1.0, v136
	v_add_f32_e32 v137, 1.0, v137
	v_rcp_f32_e32 v136, v136
	v_rcp_f32_e32 v137, v137
	v_add_f32_e32 v152, 1.0, v152
	v_add_f32_e32 v153, 1.0, v153
	v_rcp_f32_e32 v152, v152
	v_rcp_f32_e32 v153, v153
	v_pk_mul_f32 v[128:129], v[128:129], v[136:137]
	v_add_u32_e32 v154, 32, v202
	v_pk_mul_f32 v[124:125], v[124:125], v[128:129]
	v_pk_mul_f32 v[128:129], v[130:131], v[152:153]
	v_cndmask_b32_e64 v130, v115, v123, s[4:5]
	v_pk_mul_f32 v[126:127], v[126:127], v[128:129]
	v_cvt_pk_bf16_f32 v128, v124, v125
	v_mad_i64_i32 v[124:125], s[36:37], v154, s76, v[138:139]
	v_cvt_pk_bf16_f32 v129, v126, v127
; DI uint2 pk4(f32x4 v) { return make_uint2(pk2(v[0], v[1]), pk2(v[2], v[3])); }
; DI float gelu_t(float x) { float u = 1.5957691216057308f * (x + 0.044715f * x * x * x); return x * __builtin_amdgcn_rcpf(1.f + __expf(-u)); }
;     DI void operator()(const f32x4 (&acc)[2][2][4][2], const pg8::Unit& u, int wr, int wc, int fr, int fq) const {
;     ...
;                 f32x4 gprev = (f32x4){0.f, 0.f, 0.f, 0.f};
; #pragma unroll
;                 for (int m = 0; m < 4; ++m) {
;                     const f32x4 v = acc[ai][bj][m][0], g = acc[ai][bj][m][1];
;                     f32x4 p1, p2;
; #pragma unroll
;                     for (int r = 0; r < 4; ++r) {
;                         p1[r] = __builtin_bit_cast(float, __builtin_amdgcn_update_dpp(0, __builtin_bit_cast(int, (fr == 15) ? gprev[r] : g[r]), 0x121, 0xF, 0xF, false));
;                         p2[r] = __builtin_bit_cast(float, __builtin_amdgcn_update_dpp(0, __builtin_bit_cast(int, (fr >= 14) ? gprev[r] : g[r]), 0x122, 0xF, 0xF, false));
;                     }
;                     const int row = u.pm * 256 + ai * 128 + wr * 64 + m * 16 + fr;
;                     const int wb = row >> 6;
;                     if (m == 0 && fr < 2) {
;                         *(f32x4*)(gfirst + ((size_t)wb * 2 + fr) * FH + hc) = g;
;                         *(f32x4*)(vfirst + ((size_t)wb * 2 + fr) * FH + hc) = v;
;                     } else {
;                         f32x4 o;
;                         o[0] = gelu_t(bb.x + w0.x * p2[0] + w1.x * p1[0] + w2.x * g[0]) * v[0];
;                         o[1] = gelu_t(bb.y + w0.y * p2[1] + w1.y * p1[1] + w2.y * g[1]) * v[1];
;                         o[2] = gelu_t(bb.z + w0.z * p2[2] + w1.z * p1[2] + w2.z * g[2]) * v[2];
;                         o[3] = gelu_t(bb.w + w0.w * p2[3] + w1.w * p1[3] + w2.w * g[3]) * v[3];
;                         *(uint2*)(hid + (size_t)row * FH + hc) = pk4(o);
;                     }
;                     if (m == 3 && fr >= 14) *(f32x4*)(glast + ((size_t)wb * 2 + (fr - 14)) * FH + hc) = g;
;                     gprev = g;
	v_lshl_add_u64 v[126:127], v[124:125], 0, v[134:135]
	global_store_dwordx2 v[126:127], v[128:129], off
	v_cndmask_b32_e64 v127, v112, v120, s[4:5]
	v_cndmask_b32_e64 v128, v113, v121, s[4:5]
	v_cndmask_b32_e64 v129, v114, v122, s[4:5]
	v_mov_b32_dpp v126, v127 row_ror:1 row_mask:0xf bank_mask:0xf
	v_cndmask_b32_e32 v127, v112, v120, vcc
	v_add_u32_e32 v136, 48, v202
	s_nop 0
	v_mov_b32_dpp v120, v127 row_ror:2 row_mask:0xf bank_mask:0xf
	s_nop 1
	v_mov_b32_dpp v127, v128 row_ror:1 row_mask:0xf bank_mask:0xf
	v_cndmask_b32_e32 v128, v113, v121, vcc
	s_nop 1
	v_mov_b32_dpp v121, v128 row_ror:2 row_mask:0xf bank_mask:0xf
	v_pk_fma_f32 v[120:121], v[140:141], v[120:121], v[156:157]
	v_pk_fma_f32 v[120:121], v[144:145], v[126:127], v[120:121]
	s_nop 0
	v_pk_fma_f32 v[126:127], v[112:113], v[148:149], v[120:121]
	v_mov_b32_dpp v128, v129 row_ror:1 row_mask:0xf bank_mask:0xf
	v_mul_f32_e32 v120, 0x3d372713, v126
	v_mul_f32_e32 v120, v126, v120
	v_mul_f32_e32 v121, 0x3d372713, v127
	v_fma_f32 v120, v126, v120, v126
	v_mul_f32_e32 v121, v127, v121
	v_mul_f32_e32 v120, 0xbfcc422a, v120
	v_fma_f32 v121, v127, v121, v127
	v_mul_f32_e32 v120, 0x3fb8aa3b, v120
	v_mul_f32_e32 v121, 0xbfcc422a, v121
	v_exp_f32_e32 v120, v120
	v_mul_f32_e32 v121, 0x3fb8aa3b, v121
	v_cndmask_b32_e32 v129, v114, v122, vcc
	v_exp_f32_e32 v121, v121
	v_add_f32_e32 v120, 1.0, v120
	v_mov_b32_dpp v122, v129 row_ror:2 row_mask:0xf bank_mask:0xf
	v_add_f32_e32 v131, 1.0, v121
	v_rcp_f32_e32 v131, v131
	v_mov_b32_dpp v129, v130 row_ror:1 row_mask:0xf bank_mask:0xf
	v_cndmask_b32_e32 v130, v115, v123, vcc
	s_nop 1
	v_mov_b32_dpp v123, v130 row_ror:2 row_mask:0xf bank_mask:0xf
	v_rcp_f32_e32 v130, v120
	v_pk_fma_f32 v[120:121], v[142:143], v[122:123], v[158:159]
	v_pk_mul_f32 v[126:127], v[126:127], v[130:131]
	v_pk_fma_f32 v[120:121], v[146:147], v[128:129], v[120:121]
	v_pk_mul_f32 v[116:117], v[116:117], v[126:127]
	v_pk_fma_f32 v[122:123], v[114:115], v[150:151], v[120:121]
	s_nop 0
	v_mul_f32_e32 v120, 0x3d372713, v122
	v_mul_f32_e32 v120, v122, v120
	v_mul_f32_e32 v121, 0x3d372713, v123
	v_fma_f32 v120, v122, v120, v122
	v_mul_f32_e32 v121, v123, v121
	v_mul_f32_e32 v120, 0xbfcc422a, v120
	v_fma_f32 v121, v123, v121, v123
	v_mul_f32_e32 v120, 0x3fb8aa3b, v120
	v_mul_f32_e32 v121, 0xbfcc422a, v121
	v_exp_f32_e32 v120, v120
	v_mul_f32_e32 v121, 0x3fb8aa3b, v121
	v_exp_f32_e32 v121, v121
	v_add_f32_e32 v120, 1.0, v120
	v_rcp_f32_e32 v128, v120
	v_add_f32_e32 v120, 1.0, v121
	v_rcp_f32_e32 v129, v120
	v_ashrrev_i32_e32 v120, 6, v136
	v_ashrrev_i32_e32 v121, 31, v120
	v_pk_mul_f32 v[122:123], v[122:123], v[128:129]
	s_nop 0
	v_pk_mul_f32 v[118:119], v[118:119], v[122:123]
	v_cvt_pk_bf16_f32 v122, v116, v117
	v_mad_i64_i32 v[116:117], s[36:37], v136, s76, v[138:139]
	v_cvt_pk_bf16_f32 v123, v118, v119
	v_lshl_add_u64 v[118:119], v[116:117], 0, v[134:135]
	global_store_dwordx2 v[118:119], v[122:123], off
	s_and_saveexec_b64 s[36:37], vcc
	s_cbranch_execz .LBB0_1070
	v_lshl_add_u64 v[118:119], v[120:121], 1, v[168:169]
	v_mov_b64_e32 v[122:123], s[68:69]
	v_mad_u64_u32 v[122:123], s[38:39], v118, s77, v[122:123]
	v_mad_i32_i24 v123, v119, s77, v123
	v_lshl_add_u64 v[118:119], v[184:185], 2, v[122:123]
	global_store_dwordx4 v[118:119], v[112:115], off
.LBB0_1070:
	s_or_b64 exec, exec, s[36:37]
	s_nop 0
	v_cndmask_b32_e64 v112, v104, 0, s[4:5]
	s_nop 1
	v_mov_b32_dpp v118, v112 row_ror:1 row_mask:0xf bank_mask:0xf
	v_cndmask_b32_e64 v112, v104, 0, vcc
	v_cndmask_b32_e64 v113, v106, 0, s[4:5]
	s_nop 0
	v_mov_b32_dpp v122, v112 row_ror:2 row_mask:0xf bank_mask:0xf
	v_cndmask_b32_e64 v112, v105, 0, s[4:5]
	v_cndmask_b32_e64 v115, v107, 0, s[4:5]
	s_nop 0
	v_mov_b32_dpp v119, v112 row_ror:1 row_mask:0xf bank_mask:0xf
	v_cndmask_b32_e64 v112, v105, 0, vcc
	v_cndmask_b32_e64 v127, v107, 0, vcc
	v_add_u32_e32 v126, 0x80, v202
	v_mov_b32_dpp v123, v112 row_ror:2 row_mask:0xf bank_mask:0xf
	s_nop 1
	v_mov_b32_dpp v112, v113 row_ror:1 row_mask:0xf bank_mask:0xf
	v_cndmask_b32_e64 v113, v106, 0, vcc
	s_nop 1
	v_mov_b32_dpp v114, v113 row_ror:2 row_mask:0xf bank_mask:0xf
	s_nop 1
	v_mov_b32_dpp v113, v115 row_ror:1 row_mask:0xf bank_mask:0xf
	s_nop 1
	v_mov_b32_dpp v115, v127 row_ror:2 row_mask:0xf bank_mask:0xf
	s_and_saveexec_b64 s[36:37], s[6:7]
	s_xor_b64 s[36:37], exec, s[36:37]
	s_cbranch_execz .LBB0_1072
	v_pk_fma_f32 v[114:115], v[142:143], v[114:115], v[158:159]
	v_pk_fma_f32 v[122:123], v[140:141], v[122:123], v[156:157]
	v_pk_fma_f32 v[112:113], v[146:147], v[112:113], v[114:115]
	v_pk_fma_f32 v[118:119], v[144:145], v[118:119], v[122:123]
	v_pk_fma_f32 v[112:113], v[106:107], v[150:151], v[112:113]
	v_pk_fma_f32 v[118:119], v[104:105], v[148:149], v[118:119]
	v_mul_f32_e32 v114, 0x3d372713, v112
	v_mul_f32_e32 v115, 0x3d372713, v113
	v_mul_f32_e32 v114, v112, v114
	v_mul_f32_e32 v115, v113, v115
	v_mul_f32_e32 v122, 0x3d372713, v118
	v_mul_f32_e32 v123, 0x3d372713, v119
	v_fma_f32 v114, v112, v114, v112
	v_fma_f32 v115, v113, v115, v113
	v_mul_f32_e32 v122, v118, v122
	v_mul_f32_e32 v123, v119, v123
	v_mul_f32_e32 v114, 0xbfcc422a, v114
	v_mul_f32_e32 v115, 0xbfcc422a, v115
	v_fma_f32 v122, v118, v122, v118
	v_fma_f32 v123, v119, v123, v119
	v_mul_f32_e32 v114, 0x3fb8aa3b, v114
	v_mul_f32_e32 v115, 0x3fb8aa3b, v115
	v_mul_f32_e32 v122, 0xbfcc422a, v122
	v_mul_f32_e32 v123, 0xbfcc422a, v123
	v_exp_f32_e32 v114, v114
	v_exp_f32_e32 v115, v115
	v_mul_f32_e32 v122, 0x3fb8aa3b, v122
	v_mul_f32_e32 v123, 0x3fb8aa3b, v123
	v_exp_f32_e32 v122, v122
	v_exp_f32_e32 v123, v123
	v_add_f32_e32 v114, 1.0, v114
	v_add_f32_e32 v115, 1.0, v115
	v_rcp_f32_e32 v114, v114
	v_rcp_f32_e32 v115, v115
	v_add_f32_e32 v122, 1.0, v122
	v_add_f32_e32 v123, 1.0, v123
	v_rcp_f32_e32 v122, v122
	v_rcp_f32_e32 v123, v123
	v_pk_mul_f32 v[112:113], v[112:113], v[114:115]
	v_pk_mul_f32 v[118:119], v[118:119], v[122:123]
	v_pk_mul_f32 v[112:113], v[110:111], v[112:113]
	v_pk_mul_f32 v[118:119], v[108:109], v[118:119]
	v_cvt_pk_bf16_f32 v115, v112, v113
	v_mov_b64_e32 v[112:113], s[72:73]
	v_mad_i64_i32 v[112:113], s[38:39], v126, s76, v[112:113]
	v_cvt_pk_bf16_f32 v114, v118, v119
	v_lshl_add_u64 v[112:113], v[184:185], 1, v[112:113]
	global_store_dwordx2 v[112:113], v[114:115], off

; DI uint2 pk4(f32x4 v) { return make_uint2(pk2(v[0], v[1]), pk2(v[2], v[3])); }
; DI float gelu_t(float x) { float u = 1.5957691216057308f * (x + 0.044715f * x * x * x); return x * __builtin_amdgcn_rcpf(1.f + __expf(-u)); }
;     DI void operator()(const f32x4 (&acc)[2][2][4][2], const pg8::Unit& u, int wr, int wc, int fr, int fq) const {
;     ...
;                     const f32x4 v = acc[ai][bj][m][0], g = acc[ai][bj][m][1];
;                     f32x4 p1, p2;
; #pragma unroll
;                     for (int r = 0; r < 4; ++r) {
;                         p1[r] = __builtin_bit_cast(float, __builtin_amdgcn_update_dpp(0, __builtin_bit_cast(int, (fr == 15) ? gprev[r] : g[r]), 0x121, 0xF, 0xF, false));
;                         p2[r] = __builtin_bit_cast(float, __builtin_amdgcn_update_dpp(0, __builtin_bit_cast(int, (fr >= 14) ? gprev[r] : g[r]), 0x122, 0xF, 0xF, false));
;                     }
;                     const int row = u.pm * 256 + ai * 128 + wr * 64 + m * 16 + fr;
;                     const int wb = row >> 6;
;                     if (m == 0 && fr < 2) {
;                         *(f32x4*)(gfirst + ((size_t)wb * 2 + fr) * FH + hc) = g;
;                         *(f32x4*)(vfirst + ((size_t)wb * 2 + fr) * FH + hc) = v;
;                     } else {
;                         f32x4 o;
;                         o[0] = gelu_t(bb.x + w0.x * p2[0] + w1.x * p1[0] + w2.x * g[0]) * v[0];
;                         o[1] = gelu_t(bb.y + w0.y * p2[1] + w1.y * p1[1] + w2.y * g[1]) * v[1];
;                         o[2] = gelu_t(bb.z + w0.z * p2[2] + w1.z * p1[2] + w2.z * g[2]) * v[2];
;                         o[3] = gelu_t(bb.w + w0.w * p2[3] + w1.w * p1[3] + w2.w * g[3]) * v[3];
;                         *(uint2*)(hid + (size_t)row * FH + hc) = pk4(o);
.LBB0_1074:
	s_or_b64 exec, exec, s[36:37]
	s_nop 0
	v_cndmask_b32_e64 v109, v96, v104, s[4:5]
	v_cndmask_b32_e64 v110, v97, v105, s[4:5]
	v_cndmask_b32_e64 v111, v98, v106, s[4:5]
	v_mov_b32_dpp v108, v109 row_ror:1 row_mask:0xf bank_mask:0xf
	v_cndmask_b32_e32 v109, v96, v104, vcc
	v_cndmask_b32_e64 v114, v99, v107, s[4:5]
	s_nop 0
	v_mov_b32_dpp v104, v109 row_ror:2 row_mask:0xf bank_mask:0xf
	s_nop 1
	v_mov_b32_dpp v109, v110 row_ror:1 row_mask:0xf bank_mask:0xf
	v_cndmask_b32_e32 v110, v97, v105, vcc
	s_nop 1
	v_mov_b32_dpp v105, v110 row_ror:2 row_mask:0xf bank_mask:0xf
	v_pk_fma_f32 v[104:105], v[140:141], v[104:105], v[156:157]
	s_nop 0
	v_mov_b32_dpp v110, v111 row_ror:1 row_mask:0xf bank_mask:0xf
	v_cndmask_b32_e32 v111, v98, v106, vcc
	v_pk_fma_f32 v[104:105], v[144:145], v[108:109], v[104:105]
	s_nop 0
	v_mov_b32_dpp v106, v111 row_ror:2 row_mask:0xf bank_mask:0xf
	v_pk_fma_f32 v[104:105], v[96:97], v[148:149], v[104:105]
	s_nop 0
	v_mov_b32_dpp v111, v114 row_ror:1 row_mask:0xf bank_mask:0xf
	v_cndmask_b32_e32 v114, v99, v107, vcc
	v_mul_f32_e32 v108, 0x3d372713, v104
	v_mul_f32_e32 v109, 0x3d372713, v105
	v_mov_b32_dpp v107, v114 row_ror:2 row_mask:0xf bank_mask:0xf
	v_pk_fma_f32 v[106:107], v[142:143], v[106:107], v[158:159]
	v_mul_f32_e32 v108, v104, v108
	v_pk_fma_f32 v[106:107], v[146:147], v[110:111], v[106:107]
	v_mul_f32_e32 v109, v105, v109
	v_pk_fma_f32 v[106:107], v[98:99], v[150:151], v[106:107]
	v_fma_f32 v108, v104, v108, v104
	v_mul_f32_e32 v110, 0x3d372713, v106
	v_mul_f32_e32 v111, 0x3d372713, v107
	v_fma_f32 v109, v105, v109, v105
	v_mul_f32_e32 v110, v106, v110
	v_mul_f32_e32 v111, v107, v111
	v_mul_f32_e32 v108, 0xbfcc422a, v108
	v_mul_f32_e32 v109, 0xbfcc422a, v109
	v_fma_f32 v110, v106, v110, v106
	v_fma_f32 v111, v107, v111, v107
	v_mul_f32_e32 v108, 0x3fb8aa3b, v108
	v_mul_f32_e32 v109, 0x3fb8aa3b, v109
	v_mul_f32_e32 v110, 0xbfcc422a, v110
	v_mul_f32_e32 v111, 0xbfcc422a, v111
	v_exp_f32_e32 v108, v108
	v_exp_f32_e32 v109, v109
	v_mul_f32_e32 v110, 0x3fb8aa3b, v110
	v_mul_f32_e32 v111, 0x3fb8aa3b, v111
	v_exp_f32_e32 v110, v110
	v_exp_f32_e32 v111, v111
	v_add_f32_e32 v108, 1.0, v108
	v_add_f32_e32 v109, 1.0, v109
	v_rcp_f32_e32 v108, v108
	v_rcp_f32_e32 v109, v109
	v_add_f32_e32 v110, 1.0, v110
	v_add_f32_e32 v111, 1.0, v111
	v_rcp_f32_e32 v110, v110
	v_rcp_f32_e32 v111, v111
	v_pk_mul_f32 v[104:105], v[104:105], v[108:109]
	v_add_u32_e32 v114, 0x90, v202
	v_pk_mul_f32 v[100:101], v[100:101], v[104:105]
	v_pk_mul_f32 v[104:105], v[106:107], v[110:111]
	v_cndmask_b32_e64 v108, v91, v99, s[4:5]
	v_pk_mul_f32 v[102:103], v[102:103], v[104:105]
	v_cvt_pk_bf16_f32 v104, v100, v101
	v_cvt_pk_bf16_f32 v105, v102, v103
	v_mov_b64_e32 v[102:103], s[72:73]
	v_mad_i64_i32 v[100:101], s[36:37], v114, s76, v[102:103]
	v_lshl_add_u64 v[106:107], v[100:101], 0, v[134:135]
	global_store_dwordx2 v[106:107], v[104:105], off
	v_cndmask_b32_e64 v105, v88, v96, s[4:5]
	v_cndmask_b32_e64 v106, v89, v97, s[4:5]
	v_cndmask_b32_e64 v107, v90, v98, s[4:5]
	v_mov_b32_dpp v104, v105 row_ror:1 row_mask:0xf bank_mask:0xf
	v_cndmask_b32_e32 v105, v88, v96, vcc
	s_nop 1
	v_mov_b32_dpp v96, v105 row_ror:2 row_mask:0xf bank_mask:0xf
	s_nop 1
	v_mov_b32_dpp v105, v106 row_ror:1 row_mask:0xf bank_mask:0xf
	v_cndmask_b32_e32 v106, v89, v97, vcc
	s_nop 1
	v_mov_b32_dpp v97, v106 row_ror:2 row_mask:0xf bank_mask:0xf
	v_pk_fma_f32 v[96:97], v[140:141], v[96:97], v[156:157]
	s_nop 0
	v_mov_b32_dpp v106, v107 row_ror:1 row_mask:0xf bank_mask:0xf
	v_cndmask_b32_e32 v107, v90, v98, vcc
	v_pk_fma_f32 v[96:97], v[144:145], v[104:105], v[96:97]
	s_nop 0
	v_mov_b32_dpp v98, v107 row_ror:2 row_mask:0xf bank_mask:0xf
	v_pk_fma_f32 v[96:97], v[88:89], v[148:149], v[96:97]
	s_nop 0
	v_mov_b32_dpp v107, v108 row_ror:1 row_mask:0xf bank_mask:0xf
	v_cndmask_b32_e32 v108, v91, v99, vcc
	v_mul_f32_e32 v104, 0x3d372713, v96
	v_mul_f32_e32 v105, 0x3d372713, v97
	v_mov_b32_dpp v99, v108 row_ror:2 row_mask:0xf bank_mask:0xf
	v_pk_fma_f32 v[98:99], v[142:143], v[98:99], v[158:159]
	v_mul_f32_e32 v104, v96, v104
	v_pk_fma_f32 v[98:99], v[146:147], v[106:107], v[98:99]
	v_mul_f32_e32 v105, v97, v105
	v_pk_fma_f32 v[98:99], v[90:91], v[150:151], v[98:99]
	v_fma_f32 v104, v96, v104, v96
	v_mul_f32_e32 v106, 0x3d372713, v98
	v_mul_f32_e32 v107, 0x3d372713, v99
	v_fma_f32 v105, v97, v105, v97
	v_mul_f32_e32 v106, v98, v106
	v_mul_f32_e32 v107, v99, v107
	v_mul_f32_e32 v104, 0xbfcc422a, v104
	v_mul_f32_e32 v105, 0xbfcc422a, v105
	v_fma_f32 v106, v98, v106, v98
	v_fma_f32 v107, v99, v107, v99
	v_mul_f32_e32 v104, 0x3fb8aa3b, v104
	v_mul_f32_e32 v105, 0x3fb8aa3b, v105
	v_mul_f32_e32 v106, 0xbfcc422a, v106
	v_mul_f32_e32 v107, 0xbfcc422a, v107
	v_exp_f32_e32 v104, v104
	v_exp_f32_e32 v105, v105
	v_mul_f32_e32 v106, 0x3fb8aa3b, v106
	v_mul_f32_e32 v107, 0x3fb8aa3b, v107
	v_exp_f32_e32 v106, v106
	v_exp_f32_e32 v107, v107
	v_add_f32_e32 v104, 1.0, v104
	v_add_f32_e32 v105, 1.0, v105
	v_rcp_f32_e32 v104, v104
	v_rcp_f32_e32 v105, v105
	v_add_f32_e32 v106, 1.0, v106
	v_add_f32_e32 v107, 1.0, v107
	v_rcp_f32_e32 v106, v106
	v_rcp_f32_e32 v107, v107
	v_pk_mul_f32 v[96:97], v[96:97], v[104:105]
	v_add_u32_e32 v108, 0xa0, v202
	v_pk_mul_f32 v[92:93], v[92:93], v[96:97]
	v_pk_mul_f32 v[96:97], v[98:99], v[106:107]
	v_cndmask_b32_e64 v98, v83, v91, s[4:5]
	v_pk_mul_f32 v[94:95], v[94:95], v[96:97]
	v_cvt_pk_bf16_f32 v96, v92, v93
	v_mad_i64_i32 v[92:93], s[36:37], v108, s76, v[102:103]
	v_cvt_pk_bf16_f32 v97, v94, v95
	v_lshl_add_u64 v[94:95], v[92:93], 0, v[134:135]
	global_store_dwordx2 v[94:95], v[96:97], off
	v_cndmask_b32_e64 v95, v80, v88, s[4:5]
; DI uint2 pk4(f32x4 v) { return make_uint2(pk2(v[0], v[1]), pk2(v[2], v[3])); }
; DI float gelu_t(float x) { float u = 1.5957691216057308f * (x + 0.044715f * x * x * x); return x * __builtin_amdgcn_rcpf(1.f + __expf(-u)); }
;     DI void operator()(const f32x4 (&acc)[2][2][4][2], const pg8::Unit& u, int wr, int wc, int fr, int fq) const {
;     ...
;                 f32x4 gprev = (f32x4){0.f, 0.f, 0.f, 0.f};
; #pragma unroll
;                 for (int m = 0; m < 4; ++m) {
;                     const f32x4 v = acc[ai][bj][m][0], g = acc[ai][bj][m][1];
;                     f32x4 p1, p2;
; #pragma unroll
;                     for (int r = 0; r < 4; ++r) {
;                         p1[r] = __builtin_bit_cast(float, __builtin_amdgcn_update_dpp(0, __builtin_bit_cast(int, (fr == 15) ? gprev[r] : g[r]), 0x121, 0xF, 0xF, false));
;                         p2[r] = __builtin_bit_cast(float, __builtin_amdgcn_update_dpp(0, __builtin_bit_cast(int, (fr >= 14) ? gprev[r] : g[r]), 0x122, 0xF, 0xF, false));
;                     }
;                     const int row = u.pm * 256 + ai * 128 + wr * 64 + m * 16 + fr;
;                     const int wb = row >> 6;
;                     if (m == 0 && fr < 2) {
;                         *(f32x4*)(gfirst + ((size_t)wb * 2 + fr) * FH + hc) = g;
;                         *(f32x4*)(vfirst + ((size_t)wb * 2 + fr) * FH + hc) = v;
;                     } else {
;                         f32x4 o;
;                         o[0] = gelu_t(bb.x + w0.x * p2[0] + w1.x * p1[0] + w2.x * g[0]) * v[0];
;                         o[1] = gelu_t(bb.y + w0.y * p2[1] + w1.y * p1[1] + w2.y * g[1]) * v[1];
;                         o[2] = gelu_t(bb.z + w0.z * p2[2] + w1.z * p1[2] + w2.z * g[2]) * v[2];
;                         o[3] = gelu_t(bb.w + w0.w * p2[3] + w1.w * p1[3] + w2.w * g[3]) * v[3];
;                         *(uint2*)(hid + (size_t)row * FH + hc) = pk4(o);
;                     }
;                     if (m == 3 && fr >= 14) *(f32x4*)(glast + ((size_t)wb * 2 + (fr - 14)) * FH + hc) = g;
;                     gprev = g;
	v_cndmask_b32_e64 v96, v81, v89, s[4:5]
	v_cndmask_b32_e64 v97, v82, v90, s[4:5]
	v_mov_b32_dpp v94, v95 row_ror:1 row_mask:0xf bank_mask:0xf
	v_cndmask_b32_e32 v95, v80, v88, vcc
	v_add_u32_e32 v104, 0xb0, v202
	s_nop 0
	v_mov_b32_dpp v88, v95 row_ror:2 row_mask:0xf bank_mask:0xf
	s_nop 1
	v_mov_b32_dpp v95, v96 row_ror:1 row_mask:0xf bank_mask:0xf
	v_cndmask_b32_e32 v96, v81, v89, vcc
	s_nop 1
	v_mov_b32_dpp v89, v96 row_ror:2 row_mask:0xf bank_mask:0xf
	v_pk_fma_f32 v[88:89], v[140:141], v[88:89], v[156:157]
	v_pk_fma_f32 v[88:89], v[144:145], v[94:95], v[88:89]
	s_nop 0
	v_pk_fma_f32 v[94:95], v[80:81], v[148:149], v[88:89]
	v_mov_b32_dpp v96, v97 row_ror:1 row_mask:0xf bank_mask:0xf
	v_mul_f32_e32 v88, 0x3d372713, v94
	v_mul_f32_e32 v88, v94, v88
	v_mul_f32_e32 v89, 0x3d372713, v95
	v_fma_f32 v88, v94, v88, v94
	v_mul_f32_e32 v89, v95, v89
	v_mul_f32_e32 v88, 0xbfcc422a, v88
	v_fma_f32 v89, v95, v89, v95
	v_mul_f32_e32 v88, 0x3fb8aa3b, v88
	v_mul_f32_e32 v89, 0xbfcc422a, v89
	v_exp_f32_e32 v88, v88
	v_mul_f32_e32 v89, 0x3fb8aa3b, v89
	v_cndmask_b32_e32 v97, v82, v90, vcc
	v_exp_f32_e32 v89, v89
	v_add_f32_e32 v88, 1.0, v88
	v_mov_b32_dpp v90, v97 row_ror:2 row_mask:0xf bank_mask:0xf
	v_add_f32_e32 v99, 1.0, v89
	v_rcp_f32_e32 v99, v99
	v_mov_b32_dpp v97, v98 row_ror:1 row_mask:0xf bank_mask:0xf
	v_cndmask_b32_e32 v98, v83, v91, vcc
	s_nop 1
	v_mov_b32_dpp v91, v98 row_ror:2 row_mask:0xf bank_mask:0xf
	v_rcp_f32_e32 v98, v88
	v_pk_fma_f32 v[88:89], v[142:143], v[90:91], v[158:159]
	v_pk_mul_f32 v[94:95], v[94:95], v[98:99]
	v_pk_fma_f32 v[88:89], v[146:147], v[96:97], v[88:89]
	v_pk_mul_f32 v[84:85], v[84:85], v[94:95]
	v_pk_fma_f32 v[90:91], v[82:83], v[150:151], v[88:89]
	s_nop 0
	v_mul_f32_e32 v88, 0x3d372713, v90
	v_mul_f32_e32 v88, v90, v88
	v_mul_f32_e32 v89, 0x3d372713, v91
	v_fma_f32 v88, v90, v88, v90
	v_mul_f32_e32 v89, v91, v89
	v_mul_f32_e32 v88, 0xbfcc422a, v88
	v_fma_f32 v89, v91, v89, v91
	v_mul_f32_e32 v88, 0x3fb8aa3b, v88
	v_mul_f32_e32 v89, 0xbfcc422a, v89
	v_exp_f32_e32 v88, v88
	v_mul_f32_e32 v89, 0x3fb8aa3b, v89
	v_exp_f32_e32 v89, v89
	v_add_f32_e32 v88, 1.0, v88
	v_rcp_f32_e32 v96, v88
	v_add_f32_e32 v88, 1.0, v89
	v_rcp_f32_e32 v97, v88
	v_ashrrev_i32_e32 v88, 6, v104
	v_ashrrev_i32_e32 v89, 31, v88
	v_pk_mul_f32 v[90:91], v[90:91], v[96:97]
	s_nop 0
	v_pk_mul_f32 v[86:87], v[86:87], v[90:91]
	v_cvt_pk_bf16_f32 v90, v84, v85
	v_mad_i64_i32 v[84:85], s[36:37], v104, s76, v[102:103]
	v_cvt_pk_bf16_f32 v91, v86, v87
	v_lshl_add_u64 v[86:87], v[84:85], 0, v[134:135]
	global_store_dwordx2 v[86:87], v[90:91], off
	s_and_saveexec_b64 s[36:37], vcc
	s_cbranch_execz .LBB0_1076
	v_lshl_add_u64 v[86:87], v[88:89], 1, v[168:169]
	v_mov_b64_e32 v[90:91], s[68:69]
	v_mad_u64_u32 v[90:91], s[38:39], v86, s77, v[90:91]
	v_mad_i32_i24 v91, v87, s77, v91
	v_lshl_add_u64 v[86:87], v[184:185], 2, v[90:91]
	global_store_dwordx4 v[86:87], v[80:83], off
.LBB0_1076:
	s_or_b64 exec, exec, s[36:37]
	s_nop 0
	v_cndmask_b32_e64 v80, v56, 0, s[4:5]
	s_nop 1
	v_mov_b32_dpp v86, v80 row_ror:1 row_mask:0xf bank_mask:0xf
	v_cndmask_b32_e64 v80, v56, 0, vcc
	v_cndmask_b32_e64 v81, v58, 0, s[4:5]
	s_nop 0
	v_mov_b32_dpp v90, v80 row_ror:2 row_mask:0xf bank_mask:0xf
	v_cndmask_b32_e64 v80, v57, 0, s[4:5]
	v_cndmask_b32_e64 v83, v59, 0, s[4:5]
	s_nop 0
	v_mov_b32_dpp v87, v80 row_ror:1 row_mask:0xf bank_mask:0xf
	v_cndmask_b32_e64 v80, v57, 0, vcc
	v_cndmask_b32_e64 v94, v59, 0, vcc
	s_nop 0
	v_mov_b32_dpp v91, v80 row_ror:2 row_mask:0xf bank_mask:0xf
	s_nop 1
	v_mov_b32_dpp v80, v81 row_ror:1 row_mask:0xf bank_mask:0xf
	v_cndmask_b32_e64 v81, v58, 0, vcc
	s_nop 1
	v_mov_b32_dpp v82, v81 row_ror:2 row_mask:0xf bank_mask:0xf
	s_nop 1
	v_mov_b32_dpp v81, v83 row_ror:1 row_mask:0xf bank_mask:0xf
	s_nop 1
	v_mov_b32_dpp v83, v94 row_ror:2 row_mask:0xf bank_mask:0xf
	s_and_saveexec_b64 s[36:37], s[6:7]
	s_xor_b64 s[36:37], exec, s[36:37]
	s_cbranch_execz .LBB0_1078
	v_pk_fma_f32 v[82:83], v[70:71], v[82:83], v[78:79]
	v_pk_fma_f32 v[90:91], v[68:69], v[90:91], v[76:77]
	v_pk_fma_f32 v[80:81], v[74:75], v[80:81], v[82:83]
	v_pk_fma_f32 v[86:87], v[72:73], v[86:87], v[90:91]
	v_pk_fma_f32 v[80:81], v[58:59], v[66:67], v[80:81]
	v_pk_fma_f32 v[86:87], v[56:57], v[64:65], v[86:87]
	v_mul_f32_e32 v82, 0x3d372713, v80
	v_mul_f32_e32 v83, 0x3d372713, v81
	v_mul_f32_e32 v82, v80, v82
	v_mul_f32_e32 v83, v81, v83
	v_mul_f32_e32 v90, 0x3d372713, v86
	v_mul_f32_e32 v91, 0x3d372713, v87
	v_fma_f32 v82, v80, v82, v80
	v_fma_f32 v83, v81, v83, v81
	v_mul_f32_e32 v90, v86, v90
	v_mul_f32_e32 v91, v87, v91
	v_mul_f32_e32 v82, 0xbfcc422a, v82
	v_mul_f32_e32 v83, 0xbfcc422a, v83
	v_fma_f32 v90, v86, v90, v86
	v_fma_f32 v91, v87, v91, v87
	v_mul_f32_e32 v82, 0x3fb8aa3b, v82
	v_mul_f32_e32 v83, 0x3fb8aa3b, v83
	v_mul_f32_e32 v90, 0xbfcc422a, v90
	v_mul_f32_e32 v91, 0xbfcc422a, v91
	v_exp_f32_e32 v82, v82
	v_exp_f32_e32 v83, v83
	v_mul_f32_e32 v90, 0x3fb8aa3b, v90
	v_mul_f32_e32 v91, 0x3fb8aa3b, v91
	v_exp_f32_e32 v90, v90
	v_exp_f32_e32 v91, v91
	v_add_f32_e32 v82, 1.0, v82
	v_add_f32_e32 v83, 1.0, v83
	v_rcp_f32_e32 v82, v82
	v_rcp_f32_e32 v83, v83
	v_add_f32_e32 v90, 1.0, v90
	v_add_f32_e32 v91, 1.0, v91
	v_rcp_f32_e32 v90, v90
	v_rcp_f32_e32 v91, v91
	v_pk_mul_f32 v[80:81], v[80:81], v[82:83]
	v_pk_mul_f32 v[86:87], v[86:87], v[90:91]
	v_pk_mul_f32 v[80:81], v[62:63], v[80:81]
	v_pk_mul_f32 v[86:87], v[60:61], v[86:87]
	v_cvt_pk_bf16_f32 v83, v80, v81
	v_mov_b64_e32 v[80:81], s[72:73]
	v_mad_i64_i32 v[80:81], s[38:39], v202, s76, v[80:81]
	v_cvt_pk_bf16_f32 v82, v86, v87
	v_lshl_add_u64 v[80:81], v[178:179], 1, v[80:81]
	global_store_dwordx2 v[80:81], v[82:83], off

; DI uint2 pk4(f32x4 v) { return make_uint2(pk2(v[0], v[1]), pk2(v[2], v[3])); }
; DI float gelu_t(float x) { float u = 1.5957691216057308f * (x + 0.044715f * x * x * x); return x * __builtin_amdgcn_rcpf(1.f + __expf(-u)); }
;     DI void operator()(const f32x4 (&acc)[2][2][4][2], const pg8::Unit& u, int wr, int wc, int fr, int fq) const {
;     ...
;                     const f32x4 v = acc[ai][bj][m][0], g = acc[ai][bj][m][1];
;                     f32x4 p1, p2;
; #pragma unroll
;                     for (int r = 0; r < 4; ++r) {
;                         p1[r] = __builtin_bit_cast(float, __builtin_amdgcn_update_dpp(0, __builtin_bit_cast(int, (fr == 15) ? gprev[r] : g[r]), 0x121, 0xF, 0xF, false));
;                         p2[r] = __builtin_bit_cast(float, __builtin_amdgcn_update_dpp(0, __builtin_bit_cast(int, (fr >= 14) ? gprev[r] : g[r]), 0x122, 0xF, 0xF, false));
;                     }
;                     const int row = u.pm * 256 + ai * 128 + wr * 64 + m * 16 + fr;
;                     const int wb = row >> 6;
;                     if (m == 0 && fr < 2) {
;                         *(f32x4*)(gfirst + ((size_t)wb * 2 + fr) * FH + hc) = g;
;                         *(f32x4*)(vfirst + ((size_t)wb * 2 + fr) * FH + hc) = v;
;                     } else {
;                         f32x4 o;
;                         o[0] = gelu_t(bb.x + w0.x * p2[0] + w1.x * p1[0] + w2.x * g[0]) * v[0];
;                         o[1] = gelu_t(bb.y + w0.y * p2[1] + w1.y * p1[1] + w2.y * g[1]) * v[1];
;                         o[2] = gelu_t(bb.z + w0.z * p2[2] + w1.z * p1[2] + w2.z * g[2]) * v[2];
;                         o[3] = gelu_t(bb.w + w0.w * p2[3] + w1.w * p1[3] + w2.w * g[3]) * v[3];
;                         *(uint2*)(hid + (size_t)row * FH + hc) = pk4(o);
.LBB0_1080:
	s_or_b64 exec, exec, s[36:37]
	s_nop 0
	v_cndmask_b32_e64 v61, v48, v56, s[4:5]
	v_cndmask_b32_e64 v62, v49, v57, s[4:5]
	v_cndmask_b32_e64 v63, v50, v58, s[4:5]
	v_mov_b32_dpp v60, v61 row_ror:1 row_mask:0xf bank_mask:0xf
	v_cndmask_b32_e32 v61, v48, v56, vcc
	v_cndmask_b32_e64 v80, v51, v59, s[4:5]
	s_nop 0
	v_mov_b32_dpp v56, v61 row_ror:2 row_mask:0xf bank_mask:0xf
	s_nop 1
	v_mov_b32_dpp v61, v62 row_ror:1 row_mask:0xf bank_mask:0xf
	v_cndmask_b32_e32 v62, v49, v57, vcc
	s_nop 1
	v_mov_b32_dpp v57, v62 row_ror:2 row_mask:0xf bank_mask:0xf
	v_pk_fma_f32 v[56:57], v[68:69], v[56:57], v[76:77]
	s_nop 0
	v_mov_b32_dpp v62, v63 row_ror:1 row_mask:0xf bank_mask:0xf
	v_cndmask_b32_e32 v63, v50, v58, vcc
	v_pk_fma_f32 v[56:57], v[72:73], v[60:61], v[56:57]
	s_nop 0
	v_mov_b32_dpp v58, v63 row_ror:2 row_mask:0xf bank_mask:0xf
	v_pk_fma_f32 v[56:57], v[48:49], v[64:65], v[56:57]
	s_nop 0
	v_mov_b32_dpp v63, v80 row_ror:1 row_mask:0xf bank_mask:0xf
	v_cndmask_b32_e32 v80, v51, v59, vcc
	v_mul_f32_e32 v60, 0x3d372713, v56
	v_mul_f32_e32 v61, 0x3d372713, v57
	v_mov_b32_dpp v59, v80 row_ror:2 row_mask:0xf bank_mask:0xf
	v_pk_fma_f32 v[58:59], v[70:71], v[58:59], v[78:79]
	v_mul_f32_e32 v60, v56, v60
	v_pk_fma_f32 v[58:59], v[74:75], v[62:63], v[58:59]
	v_mul_f32_e32 v61, v57, v61
	v_pk_fma_f32 v[58:59], v[50:51], v[66:67], v[58:59]
	v_fma_f32 v60, v56, v60, v56
	v_mul_f32_e32 v62, 0x3d372713, v58
	v_mul_f32_e32 v63, 0x3d372713, v59
	v_fma_f32 v61, v57, v61, v57
	v_mul_f32_e32 v62, v58, v62
	v_mul_f32_e32 v63, v59, v63
	v_mul_f32_e32 v60, 0xbfcc422a, v60
	v_mul_f32_e32 v61, 0xbfcc422a, v61
	v_fma_f32 v62, v58, v62, v58
	v_fma_f32 v63, v59, v63, v59
	v_mul_f32_e32 v60, 0x3fb8aa3b, v60
	v_mul_f32_e32 v61, 0x3fb8aa3b, v61
	v_mul_f32_e32 v62, 0xbfcc422a, v62
	v_mul_f32_e32 v63, 0xbfcc422a, v63
	v_exp_f32_e32 v60, v60
	v_exp_f32_e32 v61, v61
	v_mul_f32_e32 v62, 0x3fb8aa3b, v62
	v_mul_f32_e32 v63, 0x3fb8aa3b, v63
	v_exp_f32_e32 v62, v62
	v_exp_f32_e32 v63, v63
	v_add_f32_e32 v60, 1.0, v60
	v_add_f32_e32 v61, 1.0, v61
	v_rcp_f32_e32 v60, v60
	v_rcp_f32_e32 v61, v61
	v_add_f32_e32 v62, 1.0, v62
	v_add_f32_e32 v63, 1.0, v63
	v_rcp_f32_e32 v62, v62
	v_rcp_f32_e32 v63, v63
	v_pk_mul_f32 v[56:57], v[56:57], v[60:61]
	v_cndmask_b32_e64 v60, v41, v49, s[4:5]
	v_pk_mul_f32 v[52:53], v[52:53], v[56:57]
	v_pk_mul_f32 v[56:57], v[58:59], v[62:63]
	v_cndmask_b32_e64 v59, v40, v48, s[4:5]
	v_cndmask_b32_e64 v61, v42, v50, s[4:5]
	v_cndmask_b32_e64 v62, v43, v51, s[4:5]
	v_mov_b32_dpp v58, v59 row_ror:1 row_mask:0xf bank_mask:0xf
	v_cndmask_b32_e32 v59, v40, v48, vcc
	v_pk_mul_f32 v[54:55], v[54:55], v[56:57]
	v_cvt_pk_bf16_f32 v56, v52, v53
	v_mov_b32_dpp v48, v59 row_ror:2 row_mask:0xf bank_mask:0xf
	v_lshlrev_b64 v[52:53], 1, v[178:179]
	v_cvt_pk_bf16_f32 v57, v54, v55
	v_mov_b32_dpp v59, v60 row_ror:1 row_mask:0xf bank_mask:0xf
	v_cndmask_b32_e32 v60, v41, v49, vcc
	v_lshl_add_u64 v[54:55], v[132:133], 0, v[52:53]
	global_store_dwordx2 v[54:55], v[56:57], off
	v_mov_b32_dpp v49, v60 row_ror:2 row_mask:0xf bank_mask:0xf
	v_pk_fma_f32 v[48:49], v[68:69], v[48:49], v[76:77]
	v_cndmask_b32_e64 v54, v35, v43, s[4:5]
	v_mov_b32_dpp v60, v61 row_ror:1 row_mask:0xf bank_mask:0xf
	v_cndmask_b32_e32 v61, v42, v50, vcc
	v_pk_fma_f32 v[48:49], v[72:73], v[58:59], v[48:49]
	s_nop 0
	v_mov_b32_dpp v50, v61 row_ror:2 row_mask:0xf bank_mask:0xf
	v_pk_fma_f32 v[48:49], v[40:41], v[64:65], v[48:49]
	s_nop 0
	v_mov_b32_dpp v61, v62 row_ror:1 row_mask:0xf bank_mask:0xf
	v_cndmask_b32_e32 v62, v43, v51, vcc
	v_mul_f32_e32 v58, 0x3d372713, v48
	v_mul_f32_e32 v59, 0x3d372713, v49
	v_mov_b32_dpp v51, v62 row_ror:2 row_mask:0xf bank_mask:0xf
	v_pk_fma_f32 v[50:51], v[70:71], v[50:51], v[78:79]
	v_mul_f32_e32 v58, v48, v58
	v_pk_fma_f32 v[50:51], v[74:75], v[60:61], v[50:51]
	v_mul_f32_e32 v59, v49, v59
	v_pk_fma_f32 v[50:51], v[42:43], v[66:67], v[50:51]
	v_fma_f32 v58, v48, v58, v48
	v_mul_f32_e32 v60, 0x3d372713, v50
	v_mul_f32_e32 v61, 0x3d372713, v51
	v_fma_f32 v59, v49, v59, v49
	v_mul_f32_e32 v60, v50, v60
	v_mul_f32_e32 v61, v51, v61
	v_mul_f32_e32 v58, 0xbfcc422a, v58
	v_mul_f32_e32 v59, 0xbfcc422a, v59
	v_fma_f32 v60, v50, v60, v50
	v_fma_f32 v61, v51, v61, v51
	v_mul_f32_e32 v58, 0x3fb8aa3b, v58
	v_mul_f32_e32 v59, 0x3fb8aa3b, v59
	v_mul_f32_e32 v60, 0xbfcc422a, v60
	v_mul_f32_e32 v61, 0xbfcc422a, v61
	v_exp_f32_e32 v58, v58
	v_exp_f32_e32 v59, v59
	v_mul_f32_e32 v60, 0x3fb8aa3b, v60
	v_mul_f32_e32 v61, 0x3fb8aa3b, v61
	v_exp_f32_e32 v60, v60
	v_exp_f32_e32 v61, v61
	v_add_f32_e32 v58, 1.0, v58
	v_add_f32_e32 v59, 1.0, v59
	v_rcp_f32_e32 v58, v58
	v_rcp_f32_e32 v59, v59
	v_add_f32_e32 v60, 1.0, v60
	v_add_f32_e32 v61, 1.0, v61
	v_rcp_f32_e32 v60, v60
	v_rcp_f32_e32 v61, v61
	v_pk_mul_f32 v[48:49], v[48:49], v[58:59]
	s_nop 0
	v_pk_mul_f32 v[44:45], v[44:45], v[48:49]
	v_pk_mul_f32 v[48:49], v[50:51], v[60:61]
	v_cndmask_b32_e64 v50, v33, v41, s[4:5]
	v_pk_mul_f32 v[46:47], v[46:47], v[48:49]
	v_cndmask_b32_e64 v49, v32, v40, s[4:5]
	v_cndmask_b32_e64 v51, v34, v42, s[4:5]
	v_cvt_pk_bf16_f32 v44, v44, v45
	v_mov_b32_dpp v48, v49 row_ror:1 row_mask:0xf bank_mask:0xf
	v_cndmask_b32_e32 v49, v32, v40, vcc
	v_cvt_pk_bf16_f32 v45, v46, v47
	v_lshl_add_u64 v[46:47], v[124:125], 0, v[52:53]
	v_mov_b32_dpp v40, v49 row_ror:2 row_mask:0xf bank_mask:0xf
; DI uint2 pk4(f32x4 v) { return make_uint2(pk2(v[0], v[1]), pk2(v[2], v[3])); }
; DI float gelu_t(float x) { float u = 1.5957691216057308f * (x + 0.044715f * x * x * x); return x * __builtin_amdgcn_rcpf(1.f + __expf(-u)); }
;     DI void operator()(const f32x4 (&acc)[2][2][4][2], const pg8::Unit& u, int wr, int wc, int fr, int fq) const {
;     ...
;                 f32x4 gprev = (f32x4){0.f, 0.f, 0.f, 0.f};
; #pragma unroll
;                 for (int m = 0; m < 4; ++m) {
;                     const f32x4 v = acc[ai][bj][m][0], g = acc[ai][bj][m][1];
;                     f32x4 p1, p2;
; #pragma unroll
;                     for (int r = 0; r < 4; ++r) {
;                         p1[r] = __builtin_bit_cast(float, __builtin_amdgcn_update_dpp(0, __builtin_bit_cast(int, (fr == 15) ? gprev[r] : g[r]), 0x121, 0xF, 0xF, false));
;                         p2[r] = __builtin_bit_cast(float, __builtin_amdgcn_update_dpp(0, __builtin_bit_cast(int, (fr >= 14) ? gprev[r] : g[r]), 0x122, 0xF, 0xF, false));
;                     }
;                     const int row = u.pm * 256 + ai * 128 + wr * 64 + m * 16 + fr;
;                     const int wb = row >> 6;
;                     if (m == 0 && fr < 2) {
;                         *(f32x4*)(gfirst + ((size_t)wb * 2 + fr) * FH + hc) = g;
;                         *(f32x4*)(vfirst + ((size_t)wb * 2 + fr) * FH + hc) = v;
;                     } else {
;                         f32x4 o;
;                         o[0] = gelu_t(bb.x + w0.x * p2[0] + w1.x * p1[0] + w2.x * g[0]) * v[0];
;                         o[1] = gelu_t(bb.y + w0.y * p2[1] + w1.y * p1[1] + w2.y * g[1]) * v[1];
;                         o[2] = gelu_t(bb.z + w0.z * p2[2] + w1.z * p1[2] + w2.z * g[2]) * v[2];
;                         o[3] = gelu_t(bb.w + w0.w * p2[3] + w1.w * p1[3] + w2.w * g[3]) * v[3];
;                         *(uint2*)(hid + (size_t)row * FH + hc) = pk4(o);
;                     }
;                     if (m == 3 && fr >= 14) *(f32x4*)(glast + ((size_t)wb * 2 + (fr - 14)) * FH + hc) = g;
;                     gprev = g;
	global_store_dwordx2 v[46:47], v[44:45], off
	s_nop 0
	v_mov_b32_dpp v49, v50 row_ror:1 row_mask:0xf bank_mask:0xf
	v_cndmask_b32_e32 v50, v33, v41, vcc
	s_nop 1
	v_mov_b32_dpp v41, v50 row_ror:2 row_mask:0xf bank_mask:0xf
	v_pk_fma_f32 v[40:41], v[68:69], v[40:41], v[76:77]
	s_nop 0
	v_mov_b32_dpp v50, v51 row_ror:1 row_mask:0xf bank_mask:0xf
	v_cndmask_b32_e32 v51, v34, v42, vcc
	v_pk_fma_f32 v[40:41], v[72:73], v[48:49], v[40:41]
	s_nop 0
	v_mov_b32_dpp v42, v51 row_ror:2 row_mask:0xf bank_mask:0xf
	v_pk_fma_f32 v[40:41], v[32:33], v[64:65], v[40:41]
	s_nop 0
	v_mov_b32_dpp v51, v54 row_ror:1 row_mask:0xf bank_mask:0xf
	v_cndmask_b32_e32 v54, v35, v43, vcc
	v_mul_f32_e32 v48, 0x3d372713, v40
	v_mul_f32_e32 v49, 0x3d372713, v41
	v_mov_b32_dpp v43, v54 row_ror:2 row_mask:0xf bank_mask:0xf
	v_pk_fma_f32 v[42:43], v[70:71], v[42:43], v[78:79]
	v_mul_f32_e32 v48, v40, v48
	v_pk_fma_f32 v[42:43], v[74:75], v[50:51], v[42:43]
	v_mul_f32_e32 v49, v41, v49
	v_pk_fma_f32 v[42:43], v[34:35], v[66:67], v[42:43]
	v_fma_f32 v48, v40, v48, v40
	v_mul_f32_e32 v50, 0x3d372713, v42
	v_mul_f32_e32 v51, 0x3d372713, v43
	v_fma_f32 v49, v41, v49, v41
	v_mul_f32_e32 v50, v42, v50
	v_mul_f32_e32 v51, v43, v51
	v_mul_f32_e32 v48, 0xbfcc422a, v48
	v_mul_f32_e32 v49, 0xbfcc422a, v49
	v_fma_f32 v50, v42, v50, v42
	v_fma_f32 v51, v43, v51, v43
	v_mul_f32_e32 v48, 0x3fb8aa3b, v48
	v_mul_f32_e32 v49, 0x3fb8aa3b, v49
	v_mul_f32_e32 v50, 0xbfcc422a, v50
	v_mul_f32_e32 v51, 0xbfcc422a, v51
	v_exp_f32_e32 v48, v48
	v_exp_f32_e32 v49, v49
	v_mul_f32_e32 v50, 0x3fb8aa3b, v50
	v_mul_f32_e32 v51, 0x3fb8aa3b, v51
	v_exp_f32_e32 v50, v50
	v_exp_f32_e32 v51, v51
	v_add_f32_e32 v48, 1.0, v48
	v_add_f32_e32 v49, 1.0, v49
	v_rcp_f32_e32 v48, v48
	v_rcp_f32_e32 v49, v49
	v_add_f32_e32 v50, 1.0, v50
	v_add_f32_e32 v51, 1.0, v51
	v_rcp_f32_e32 v50, v50
	v_rcp_f32_e32 v51, v51
	v_pk_mul_f32 v[40:41], v[40:41], v[48:49]
	s_nop 0
	v_pk_mul_f32 v[36:37], v[36:37], v[40:41]
	v_pk_mul_f32 v[40:41], v[42:43], v[50:51]
	v_cvt_pk_bf16_f32 v36, v36, v37
	v_pk_mul_f32 v[38:39], v[38:39], v[40:41]
	s_nop 0
	v_cvt_pk_bf16_f32 v37, v38, v39
	v_lshl_add_u64 v[38:39], v[116:117], 0, v[52:53]
	global_store_dwordx2 v[38:39], v[36:37], off
	s_and_saveexec_b64 s[36:37], vcc
	s_cbranch_execz .LBB0_1082
	v_lshl_add_u64 v[36:37], v[120:121], 1, v[168:169]
	v_mov_b64_e32 v[38:39], s[68:69]
	v_mad_u64_u32 v[38:39], s[38:39], v36, s77, v[38:39]
	v_mad_i32_i24 v39, v37, s77, v39
	v_lshl_add_u64 v[36:37], v[178:179], 2, v[38:39]
	global_store_dwordx4 v[36:37], v[32:35], off
.LBB0_1082:
	s_or_b64 exec, exec, s[36:37]
	s_nop 0
	v_cndmask_b32_e64 v32, v24, 0, s[4:5]
	s_nop 1
	v_mov_b32_dpp v36, v32 row_ror:1 row_mask:0xf bank_mask:0xf
	v_cndmask_b32_e64 v32, v24, 0, vcc
	v_cndmask_b32_e64 v33, v26, 0, s[4:5]
	s_nop 0
	v_mov_b32_dpp v38, v32 row_ror:2 row_mask:0xf bank_mask:0xf
	v_cndmask_b32_e64 v32, v25, 0, s[4:5]
	v_cndmask_b32_e64 v35, v27, 0, s[4:5]
	s_nop 0
	v_mov_b32_dpp v37, v32 row_ror:1 row_mask:0xf bank_mask:0xf
	v_cndmask_b32_e64 v32, v25, 0, vcc
	v_cndmask_b32_e64 v40, v27, 0, vcc
	s_nop 0
	v_mov_b32_dpp v39, v32 row_ror:2 row_mask:0xf bank_mask:0xf
	s_nop 1
	v_mov_b32_dpp v32, v33 row_ror:1 row_mask:0xf bank_mask:0xf
	v_cndmask_b32_e64 v33, v26, 0, vcc
	s_nop 1
	v_mov_b32_dpp v34, v33 row_ror:2 row_mask:0xf bank_mask:0xf
	s_nop 1
	v_mov_b32_dpp v33, v35 row_ror:1 row_mask:0xf bank_mask:0xf
	s_nop 1
	v_mov_b32_dpp v35, v40 row_ror:2 row_mask:0xf bank_mask:0xf
	s_and_saveexec_b64 s[36:37], s[6:7]
	s_xor_b64 s[6:7], exec, s[36:37]
	s_cbranch_execz .LBB0_1084
	v_pk_fma_f32 v[34:35], v[70:71], v[34:35], v[78:79]
	v_pk_fma_f32 v[38:39], v[68:69], v[38:39], v[76:77]
	v_pk_fma_f32 v[32:33], v[74:75], v[32:33], v[34:35]
	v_pk_fma_f32 v[36:37], v[72:73], v[36:37], v[38:39]
	v_pk_fma_f32 v[32:33], v[26:27], v[66:67], v[32:33]
	v_pk_fma_f32 v[36:37], v[24:25], v[64:65], v[36:37]
	v_mul_f32_e32 v34, 0x3d372713, v32
	v_mul_f32_e32 v35, 0x3d372713, v33
	v_mul_f32_e32 v34, v32, v34
	v_mul_f32_e32 v35, v33, v35
	v_mul_f32_e32 v38, 0x3d372713, v36
	v_mul_f32_e32 v39, 0x3d372713, v37
	v_fma_f32 v34, v32, v34, v32
	v_fma_f32 v35, v33, v35, v33
	v_mul_f32_e32 v38, v36, v38
	v_mul_f32_e32 v39, v37, v39
	v_mul_f32_e32 v34, 0xbfcc422a, v34
	v_mul_f32_e32 v35, 0xbfcc422a, v35
	v_fma_f32 v38, v36, v38, v36
	v_fma_f32 v39, v37, v39, v37
	v_mul_f32_e32 v34, 0x3fb8aa3b, v34
	v_mul_f32_e32 v35, 0x3fb8aa3b, v35
	v_mul_f32_e32 v38, 0xbfcc422a, v38
	v_mul_f32_e32 v39, 0xbfcc422a, v39
	v_exp_f32_e32 v34, v34
	v_exp_f32_e32 v35, v35
	v_mul_f32_e32 v38, 0x3fb8aa3b, v38
	v_mul_f32_e32 v39, 0x3fb8aa3b, v39
	v_exp_f32_e32 v38, v38
	v_exp_f32_e32 v39, v39
	v_add_f32_e32 v34, 1.0, v34
	v_add_f32_e32 v35, 1.0, v35
	v_rcp_f32_e32 v34, v34
	v_rcp_f32_e32 v35, v35
	v_add_f32_e32 v38, 1.0, v38
	v_add_f32_e32 v39, 1.0, v39
	v_rcp_f32_e32 v38, v38
	v_rcp_f32_e32 v39, v39
	v_pk_mul_f32 v[32:33], v[32:33], v[34:35]
	v_pk_mul_f32 v[36:37], v[36:37], v[38:39]
	v_pk_mul_f32 v[32:33], v[30:31], v[32:33]
	v_pk_mul_f32 v[36:37], v[28:29], v[36:37]
	v_cvt_pk_bf16_f32 v35, v32, v33
	v_mov_b64_e32 v[32:33], s[72:73]
	v_mad_i64_i32 v[32:33], s[36:37], v126, s76, v[32:33]
	v_cvt_pk_bf16_f32 v34, v36, v37
	v_lshl_add_u64 v[32:33], v[178:179], 1, v[32:33]
	global_store_dwordx2 v[32:33], v[34:35], off

; DI uint2 pk4(f32x4 v) { return make_uint2(pk2(v[0], v[1]), pk2(v[2], v[3])); }
; DI float gelu_t(float x) { float u = 1.5957691216057308f * (x + 0.044715f * x * x * x); return x * __builtin_amdgcn_rcpf(1.f + __expf(-u)); }
;     DI void operator()(const f32x4 (&acc)[2][2][4][2], const pg8::Unit& u, int wr, int wc, int fr, int fq) const {
;     ...
;                     const f32x4 v = acc[ai][bj][m][0], g = acc[ai][bj][m][1];
;                     f32x4 p1, p2;
; #pragma unroll
;                     for (int r = 0; r < 4; ++r) {
;                         p1[r] = __builtin_bit_cast(float, __builtin_amdgcn_update_dpp(0, __builtin_bit_cast(int, (fr == 15) ? gprev[r] : g[r]), 0x121, 0xF, 0xF, false));
;                         p2[r] = __builtin_bit_cast(float, __builtin_amdgcn_update_dpp(0, __builtin_bit_cast(int, (fr >= 14) ? gprev[r] : g[r]), 0x122, 0xF, 0xF, false));
;                     }
;                     const int row = u.pm * 256 + ai * 128 + wr * 64 + m * 16 + fr;
;                     const int wb = row >> 6;
;                     if (m == 0 && fr < 2) {
;                         *(f32x4*)(gfirst + ((size_t)wb * 2 + fr) * FH + hc) = g;
;                         *(f32x4*)(vfirst + ((size_t)wb * 2 + fr) * FH + hc) = v;
;                     } else {
;                         f32x4 o;
;                         o[0] = gelu_t(bb.x + w0.x * p2[0] + w1.x * p1[0] + w2.x * g[0]) * v[0];
;                         o[1] = gelu_t(bb.y + w0.y * p2[1] + w1.y * p1[1] + w2.y * g[1]) * v[1];
;                         o[2] = gelu_t(bb.z + w0.z * p2[2] + w1.z * p1[2] + w2.z * g[2]) * v[2];
;                         o[3] = gelu_t(bb.w + w0.w * p2[3] + w1.w * p1[3] + w2.w * g[3]) * v[3];
;                         *(uint2*)(hid + (size_t)row * FH + hc) = pk4(o);
.LBB0_1086:
	s_or_b64 exec, exec, s[6:7]
	s_nop 0
	v_cndmask_b32_e64 v29, v16, v24, s[4:5]
	v_cndmask_b32_e64 v30, v17, v25, s[4:5]
	v_cndmask_b32_e64 v31, v18, v26, s[4:5]
	v_mov_b32_dpp v28, v29 row_ror:1 row_mask:0xf bank_mask:0xf
	v_cndmask_b32_e32 v29, v16, v24, vcc
	v_cndmask_b32_e64 v32, v19, v27, s[4:5]
	s_nop 0
	v_mov_b32_dpp v24, v29 row_ror:2 row_mask:0xf bank_mask:0xf
	s_nop 1
	v_mov_b32_dpp v29, v30 row_ror:1 row_mask:0xf bank_mask:0xf
	v_cndmask_b32_e32 v30, v17, v25, vcc
	s_nop 1
	v_mov_b32_dpp v25, v30 row_ror:2 row_mask:0xf bank_mask:0xf
	v_pk_fma_f32 v[24:25], v[68:69], v[24:25], v[76:77]
	s_nop 0
	v_mov_b32_dpp v30, v31 row_ror:1 row_mask:0xf bank_mask:0xf
	v_cndmask_b32_e32 v31, v18, v26, vcc
	v_pk_fma_f32 v[24:25], v[72:73], v[28:29], v[24:25]
	s_nop 0
	v_mov_b32_dpp v26, v31 row_ror:2 row_mask:0xf bank_mask:0xf
	v_pk_fma_f32 v[24:25], v[16:17], v[64:65], v[24:25]
	s_nop 0
	v_mov_b32_dpp v31, v32 row_ror:1 row_mask:0xf bank_mask:0xf
	v_cndmask_b32_e32 v32, v19, v27, vcc
	v_mul_f32_e32 v28, 0x3d372713, v24
	v_mul_f32_e32 v29, 0x3d372713, v25
	v_mov_b32_dpp v27, v32 row_ror:2 row_mask:0xf bank_mask:0xf
	v_pk_fma_f32 v[26:27], v[70:71], v[26:27], v[78:79]
	v_mul_f32_e32 v28, v24, v28
	v_pk_fma_f32 v[26:27], v[74:75], v[30:31], v[26:27]
	v_mul_f32_e32 v29, v25, v29
	v_pk_fma_f32 v[26:27], v[18:19], v[66:67], v[26:27]
	v_fma_f32 v28, v24, v28, v24
	v_mul_f32_e32 v30, 0x3d372713, v26
	v_mul_f32_e32 v31, 0x3d372713, v27
	v_fma_f32 v29, v25, v29, v25
	v_mul_f32_e32 v30, v26, v30
	v_mul_f32_e32 v31, v27, v31
	v_mul_f32_e32 v28, 0xbfcc422a, v28
	v_mul_f32_e32 v29, 0xbfcc422a, v29
	v_fma_f32 v30, v26, v30, v26
	v_fma_f32 v31, v27, v31, v27
	v_mul_f32_e32 v28, 0x3fb8aa3b, v28
	v_mul_f32_e32 v29, 0x3fb8aa3b, v29
	v_mul_f32_e32 v30, 0xbfcc422a, v30
	v_mul_f32_e32 v31, 0xbfcc422a, v31
	v_exp_f32_e32 v28, v28
	v_exp_f32_e32 v29, v29
	v_mul_f32_e32 v30, 0x3fb8aa3b, v30
	v_mul_f32_e32 v31, 0x3fb8aa3b, v31
	v_exp_f32_e32 v30, v30
	v_exp_f32_e32 v31, v31
	v_add_f32_e32 v28, 1.0, v28
	v_add_f32_e32 v29, 1.0, v29
	v_rcp_f32_e32 v28, v28
	v_rcp_f32_e32 v29, v29
	v_add_f32_e32 v30, 1.0, v30
	v_add_f32_e32 v31, 1.0, v31
	v_rcp_f32_e32 v30, v30
	v_rcp_f32_e32 v31, v31
	v_pk_mul_f32 v[24:25], v[24:25], v[28:29]
	v_cndmask_b32_e64 v28, v11, v19, s[4:5]
	v_pk_mul_f32 v[20:21], v[20:21], v[24:25]
	v_pk_mul_f32 v[24:25], v[26:27], v[30:31]
	v_cndmask_b32_e64 v26, v9, v17, s[4:5]
	v_pk_mul_f32 v[22:23], v[22:23], v[24:25]
	v_cndmask_b32_e64 v25, v8, v16, s[4:5]
	v_cndmask_b32_e64 v27, v10, v18, s[4:5]
	v_cvt_pk_bf16_f32 v20, v20, v21
	v_mov_b32_dpp v24, v25 row_ror:1 row_mask:0xf bank_mask:0xf
	v_cndmask_b32_e32 v25, v8, v16, vcc
	v_cvt_pk_bf16_f32 v21, v22, v23
	v_lshl_add_u64 v[22:23], v[100:101], 0, v[52:53]
	v_mov_b32_dpp v16, v25 row_ror:2 row_mask:0xf bank_mask:0xf
	global_store_dwordx2 v[22:23], v[20:21], off
	v_cndmask_b32_e64 v20, v3, v11, s[4:5]
	v_mov_b32_dpp v25, v26 row_ror:1 row_mask:0xf bank_mask:0xf
	v_cndmask_b32_e32 v26, v9, v17, vcc
	s_nop 1
	v_mov_b32_dpp v17, v26 row_ror:2 row_mask:0xf bank_mask:0xf
	v_pk_fma_f32 v[16:17], v[68:69], v[16:17], v[76:77]
	s_nop 0
	v_mov_b32_dpp v26, v27 row_ror:1 row_mask:0xf bank_mask:0xf
	v_cndmask_b32_e32 v27, v10, v18, vcc
	v_pk_fma_f32 v[16:17], v[72:73], v[24:25], v[16:17]
	s_nop 0
	v_mov_b32_dpp v18, v27 row_ror:2 row_mask:0xf bank_mask:0xf
	v_pk_fma_f32 v[16:17], v[8:9], v[64:65], v[16:17]
	s_nop 0
	v_mov_b32_dpp v27, v28 row_ror:1 row_mask:0xf bank_mask:0xf
	v_cndmask_b32_e32 v28, v11, v19, vcc
	v_mul_f32_e32 v24, 0x3d372713, v16
	v_mul_f32_e32 v25, 0x3d372713, v17
	v_mov_b32_dpp v19, v28 row_ror:2 row_mask:0xf bank_mask:0xf
	v_pk_fma_f32 v[18:19], v[70:71], v[18:19], v[78:79]
	v_mul_f32_e32 v24, v16, v24
	v_pk_fma_f32 v[18:19], v[74:75], v[26:27], v[18:19]
	v_mul_f32_e32 v25, v17, v25
	v_pk_fma_f32 v[18:19], v[10:11], v[66:67], v[18:19]
; DI uint2 pk4(f32x4 v) { return make_uint2(pk2(v[0], v[1]), pk2(v[2], v[3])); }
; DI float gelu_t(float x) { float u = 1.5957691216057308f * (x + 0.044715f * x * x * x); return x * __builtin_amdgcn_rcpf(1.f + __expf(-u)); }
;     DI void operator()(const f32x4 (&acc)[2][2][4][2], const pg8::Unit& u, int wr, int wc, int fr, int fq) const {
;     ...
;                     const f32x4 v = acc[ai][bj][m][0], g = acc[ai][bj][m][1];
;                     f32x4 p1, p2;
; #pragma unroll
;                     for (int r = 0; r < 4; ++r) {
;                         p1[r] = __builtin_bit_cast(float, __builtin_amdgcn_update_dpp(0, __builtin_bit_cast(int, (fr == 15) ? gprev[r] : g[r]), 0x121, 0xF, 0xF, false));
;                         p2[r] = __builtin_bit_cast(float, __builtin_amdgcn_update_dpp(0, __builtin_bit_cast(int, (fr >= 14) ? gprev[r] : g[r]), 0x122, 0xF, 0xF, false));
;                     }
;                     const int row = u.pm * 256 + ai * 128 + wr * 64 + m * 16 + fr;
;                     const int wb = row >> 6;
;                     if (m == 0 && fr < 2) {
;                         *(f32x4*)(gfirst + ((size_t)wb * 2 + fr) * FH + hc) = g;
;                         *(f32x4*)(vfirst + ((size_t)wb * 2 + fr) * FH + hc) = v;
;                     } else {
;                         f32x4 o;
;                         o[0] = gelu_t(bb.x + w0.x * p2[0] + w1.x * p1[0] + w2.x * g[0]) * v[0];
;                         o[1] = gelu_t(bb.y + w0.y * p2[1] + w1.y * p1[1] + w2.y * g[1]) * v[1];
;                         o[2] = gelu_t(bb.z + w0.z * p2[2] + w1.z * p1[2] + w2.z * g[2]) * v[2];
;                         o[3] = gelu_t(bb.w + w0.w * p2[3] + w1.w * p1[3] + w2.w * g[3]) * v[3];
;                         *(uint2*)(hid + (size_t)row * FH + hc) = pk4(o);
;                     }
;                     if (m == 3 && fr >= 14) *(f32x4*)(glast + ((size_t)wb * 2 + (fr - 14)) * FH + hc) = g;
;                     gprev = g;
	v_fma_f32 v24, v16, v24, v16
	v_mul_f32_e32 v26, 0x3d372713, v18
	v_mul_f32_e32 v27, 0x3d372713, v19
	v_fma_f32 v25, v17, v25, v17
	v_mul_f32_e32 v26, v18, v26
	v_mul_f32_e32 v27, v19, v27
	v_mul_f32_e32 v24, 0xbfcc422a, v24
	v_mul_f32_e32 v25, 0xbfcc422a, v25
	v_fma_f32 v26, v18, v26, v18
	v_fma_f32 v27, v19, v27, v19
	v_mul_f32_e32 v24, 0x3fb8aa3b, v24
	v_mul_f32_e32 v25, 0x3fb8aa3b, v25
	v_mul_f32_e32 v26, 0xbfcc422a, v26
	v_mul_f32_e32 v27, 0xbfcc422a, v27
	v_exp_f32_e32 v24, v24
	v_exp_f32_e32 v25, v25
	v_mul_f32_e32 v26, 0x3fb8aa3b, v26
	v_mul_f32_e32 v27, 0x3fb8aa3b, v27
	v_exp_f32_e32 v26, v26
	v_exp_f32_e32 v27, v27
	v_add_f32_e32 v24, 1.0, v24
	v_add_f32_e32 v25, 1.0, v25
	v_rcp_f32_e32 v24, v24
	v_rcp_f32_e32 v25, v25
	v_add_f32_e32 v26, 1.0, v26
	v_add_f32_e32 v27, 1.0, v27
	v_rcp_f32_e32 v26, v26
	v_rcp_f32_e32 v27, v27
	v_pk_mul_f32 v[16:17], v[16:17], v[24:25]
	s_nop 0
	v_pk_mul_f32 v[12:13], v[12:13], v[16:17]
	v_pk_mul_f32 v[16:17], v[18:19], v[26:27]
	v_cndmask_b32_e64 v18, v1, v9, s[4:5]
	v_pk_mul_f32 v[14:15], v[14:15], v[16:17]
	v_cndmask_b32_e64 v17, v0, v8, s[4:5]
	v_cndmask_b32_e64 v19, v2, v10, s[4:5]
	v_cvt_pk_bf16_f32 v12, v12, v13
	v_mov_b32_dpp v16, v17 row_ror:1 row_mask:0xf bank_mask:0xf
	v_cndmask_b32_e32 v17, v0, v8, vcc
	v_cvt_pk_bf16_f32 v13, v14, v15
	v_lshl_add_u64 v[14:15], v[92:93], 0, v[52:53]
	v_mov_b32_dpp v8, v17 row_ror:2 row_mask:0xf bank_mask:0xf
	global_store_dwordx2 v[14:15], v[12:13], off
	s_nop 0
	v_mov_b32_dpp v17, v18 row_ror:1 row_mask:0xf bank_mask:0xf
	v_cndmask_b32_e32 v18, v1, v9, vcc
	s_nop 1
	v_mov_b32_dpp v9, v18 row_ror:2 row_mask:0xf bank_mask:0xf
	v_pk_fma_f32 v[8:9], v[68:69], v[8:9], v[76:77]
	s_nop 0
	v_mov_b32_dpp v18, v19 row_ror:1 row_mask:0xf bank_mask:0xf
	v_cndmask_b32_e32 v19, v2, v10, vcc
	v_pk_fma_f32 v[8:9], v[72:73], v[16:17], v[8:9]
	s_nop 0
	v_mov_b32_dpp v10, v19 row_ror:2 row_mask:0xf bank_mask:0xf
	v_pk_fma_f32 v[8:9], v[0:1], v[64:65], v[8:9]
	s_nop 0
	v_mov_b32_dpp v19, v20 row_ror:1 row_mask:0xf bank_mask:0xf
	v_cndmask_b32_e32 v20, v3, v11, vcc
	v_mul_f32_e32 v16, 0x3d372713, v8
	v_mul_f32_e32 v17, 0x3d372713, v9
	v_mov_b32_dpp v11, v20 row_ror:2 row_mask:0xf bank_mask:0xf
	v_pk_fma_f32 v[10:11], v[70:71], v[10:11], v[78:79]
	v_mul_f32_e32 v16, v8, v16
	v_pk_fma_f32 v[10:11], v[74:75], v[18:19], v[10:11]
	v_mul_f32_e32 v17, v9, v17
	v_pk_fma_f32 v[10:11], v[2:3], v[66:67], v[10:11]
	v_fma_f32 v16, v8, v16, v8
	v_mul_f32_e32 v18, 0x3d372713, v10
	v_mul_f32_e32 v19, 0x3d372713, v11
	v_fma_f32 v17, v9, v17, v9
	v_mul_f32_e32 v18, v10, v18
	v_mul_f32_e32 v19, v11, v19
	v_mul_f32_e32 v16, 0xbfcc422a, v16
	v_mul_f32_e32 v17, 0xbfcc422a, v17
	v_fma_f32 v18, v10, v18, v10
	v_fma_f32 v19, v11, v19, v11
	v_mul_f32_e32 v16, 0x3fb8aa3b, v16
	v_mul_f32_e32 v17, 0x3fb8aa3b, v17
	v_mul_f32_e32 v18, 0xbfcc422a, v18
	v_mul_f32_e32 v19, 0xbfcc422a, v19
	v_exp_f32_e32 v16, v16
	v_exp_f32_e32 v17, v17
	v_mul_f32_e32 v18, 0x3fb8aa3b, v18
	v_mul_f32_e32 v19, 0x3fb8aa3b, v19
	v_exp_f32_e32 v18, v18
	v_exp_f32_e32 v19, v19
	v_add_f32_e32 v16, 1.0, v16
	v_add_f32_e32 v17, 1.0, v17
	v_rcp_f32_e32 v16, v16
	v_rcp_f32_e32 v17, v17
	v_add_f32_e32 v18, 1.0, v18
	v_add_f32_e32 v19, 1.0, v19
	v_rcp_f32_e32 v18, v18
	v_rcp_f32_e32 v19, v19
	v_pk_mul_f32 v[8:9], v[8:9], v[16:17]
	s_nop 0
	v_pk_mul_f32 v[4:5], v[4:5], v[8:9]
	v_pk_mul_f32 v[8:9], v[10:11], v[18:19]
	v_cvt_pk_bf16_f32 v4, v4, v5
	v_pk_mul_f32 v[6:7], v[6:7], v[8:9]
	s_nop 0
	v_cvt_pk_bf16_f32 v5, v6, v7
	v_lshl_add_u64 v[6:7], v[84:85], 0, v[52:53]
	global_store_dwordx2 v[6:7], v[4:5], off
	s_and_saveexec_b64 s[4:5], vcc
	s_cbranch_execz .LBB0_1088
	v_lshl_add_u64 v[4:5], v[88:89], 1, v[168:169]
	v_mov_b64_e32 v[6:7], s[68:69]
	v_mad_u64_u32 v[6:7], s[6:7], v4, s77, v[6:7]
	v_mad_i32_i24 v7, v5, s77, v7
	v_lshl_add_u64 v[4:5], v[178:179], 2, v[6:7]
	global_store_dwordx4 v[4:5], v[0:3], off
